# scan workgroups go straight to the grid barrier after the scan instead of polling the (empty) attention queues; plus prep row/transposes un-serialised, pipelined merge
# speedup vs baseline: 1.1483x; 1.0185x over previous
.LBB0_5:
	s_or_b64 exec, exec, s[22:23]
	s_load_dwordx16 s[52:67], s[0:1], 0x40
	v_and_b32_e32 v174, 63, v141
	s_cmpk_gt_i32 s2, 0xdbf
	v_lshrrev_b32_e32 v175, 6, v141
	v_mov_b32_e32 v35, 0
	v_lshlrev_b32_e32 v142, 4, v174
	v_lshlrev_b32_e32 v144, 2, v174
	s_cbranch_scc1 .LBB0_42
	v_mul_u32_u24_e32 v2, 0x104, v175
	v_lshlrev_b32_e32 v1, 9, v141
	v_mov_b32_e32 v143, v35
	v_lshlrev_b32_e32 v34, 3, v174
	v_add3_u32 v46, v2, v144, 0
	v_mul_u32_u24_e32 v2, 0x104, v174
	v_lshlrev_b32_e32 v3, 2, v175
	v_and_b32_e32 v1, 0x7e00, v1
	v_lshlrev_b32_e32 v43, 1, v175
	v_lshl_add_u64 v[36:37], s[4:5], 0, v[142:143]
	v_lshl_add_u64 v[38:39], s[6:7], 0, v[142:143]
	v_lshl_add_u64 v[40:41], s[72:73], 0, v[34:35]
	s_mov_b32 s7, 0
	v_lshl_or_b32 v47, v175, 10, v174
	v_add3_u32 v48, v2, v3, 0
	s_mov_b32 s22, 0x3a800000
	s_mov_b32 s23, 0x800000
	v_mov_b32_e32 v42, 0x358637bd
	global_load_dwordx4 v[84:87], v[38:39], off
	global_load_dwordx4 v[88:91], v[38:39], off offset:1024
	global_load_dwordx4 v[92:95], v[38:39], off offset:2048
	global_load_dwordx4 v[96:99], v[38:39], off offset:3072
	s_mov_b32 s30, s2
	s_branch .LBB0_8

.LBB0_41:
	v_lshl_add_u32 v44, s30, 4, v43
	v_ashrrev_i32_e32 v45, 31, v44
	v_lshlrev_b64 v[2:3], 12, v[44:45]
	v_lshl_add_u64 v[2:3], v[36:37], 0, v[2:3]
	global_load_dwordx4 v[30:33], v[2:3], off nt
	global_load_dwordx4 v[26:29], v[2:3], off offset:1024 nt
	global_load_dwordx4 v[22:25], v[2:3], off offset:2048 nt
	global_load_dwordx4 v[18:21], v[2:3], off offset:3072 nt
	v_add_co_u32_e32 v2, vcc, 0x1000, v2
	v_lshlrev_b64 v[44:45], 11, v[44:45]
	s_nop 0
	v_addc_co_u32_e32 v3, vcc, 0, v3, vcc
	global_load_dwordx4 v[14:17], v[2:3], off nt
	global_load_dwordx4 v[10:13], v[2:3], off offset:1024 nt
	global_load_dwordx4 v[6:9], v[2:3], off offset:2048 nt
	s_nop 0
	global_load_dwordx4 v[2:5], v[2:3], off offset:3072 nt
	s_nop 0
	v_lshl_add_u64 v[44:45], v[40:41], 0, v[44:45]
	s_waitcnt vmcnt(7)
	v_mov_b32_e32 v56, v31
	s_waitcnt vmcnt(6)
	v_mov_b32_e32 v57, v27
	s_waitcnt vmcnt(5)
	v_mov_b32_e32 v64, v23
	s_waitcnt vmcnt(4)
	v_mov_b32_e32 v65, v19
	v_mov_b32_e32 v54, v30
	v_mov_b32_e32 v55, v26
	v_mov_b32_e32 v62, v22
	v_mov_b32_e32 v63, v18
	v_pk_mul_f32 v[56:57], v[56:57], v[56:57]
	v_pk_mul_f32 v[64:65], v[64:65], v[64:65]
	v_mov_b32_e32 v58, v32
	v_mov_b32_e32 v59, v28
	v_pk_fma_f32 v[54:55], v[54:55], v[54:55], v[56:57]
	v_pk_fma_f32 v[56:57], v[62:63], v[62:63], v[64:65]
	s_waitcnt vmcnt(3)
	v_mov_b32_e32 v64, v15
	s_waitcnt vmcnt(2)
	v_mov_b32_e32 v65, v11
	v_mov_b32_e32 v60, v33
	v_mov_b32_e32 v61, v29
	v_mov_b32_e32 v66, v24
	v_mov_b32_e32 v67, v20
	v_mov_b32_e32 v62, v14
	v_mov_b32_e32 v63, v10
	s_waitcnt vmcnt(1)
	v_mov_b32_e32 v74, v7
	s_waitcnt vmcnt(0)
	v_mov_b32_e32 v75, v3
	v_pk_fma_f32 v[54:55], v[58:59], v[58:59], v[54:55]
	v_pk_mul_f32 v[58:59], v[64:65], v[64:65]
	v_mov_b32_e32 v68, v25
	v_mov_b32_e32 v69, v21
	v_mov_b32_e32 v70, v16
	v_mov_b32_e32 v71, v12
	v_mov_b32_e32 v72, v6
	v_mov_b32_e32 v73, v2
	v_pk_fma_f32 v[56:57], v[66:67], v[66:67], v[56:57]
	v_pk_mul_f32 v[64:65], v[74:75], v[74:75]
	v_pk_fma_f32 v[54:55], v[60:61], v[60:61], v[54:55]
	v_pk_fma_f32 v[58:59], v[62:63], v[62:63], v[58:59]
	v_mov_b32_e32 v76, v17
	v_mov_b32_e32 v77, v13
	v_mov_b32_e32 v78, v8
	v_mov_b32_e32 v79, v4
	v_pk_fma_f32 v[56:57], v[68:69], v[68:69], v[56:57]
	v_pk_fma_f32 v[60:61], v[72:73], v[72:73], v[64:65]
	v_pk_fma_f32 v[58:59], v[70:71], v[70:71], v[58:59]
	v_add_f32_e32 v34, v54, v55
	v_mov_b32_e32 v80, v9
	v_mov_b32_e32 v81, v5
	v_pk_fma_f32 v[54:55], v[78:79], v[78:79], v[60:61]
	v_pk_fma_f32 v[58:59], v[76:77], v[76:77], v[58:59]
	v_add_f32_e32 v34, v34, v56
	v_pk_fma_f32 v[54:55], v[80:81], v[80:81], v[54:55]
	v_add_f32_e32 v34, v34, v57
	v_add_f32_e32 v49, v58, v59
	v_add_f32_e32 v49, v49, v54
	v_mov_b32_e32 v54, v34
	v_add_f32_e32 v49, v49, v55
	s_nop 0
	v_mov_b32_dpp v54, v54 quad_perm:[1,0,3,2] row_mask:0xf bank_mask:0xf
	v_add_f32_e32 v34, v34, v54
	v_mov_b32_e32 v54, v49
	v_mov_b32_e32 v55, v34
	s_nop 0
	v_mov_b32_dpp v54, v54 quad_perm:[1,0,3,2] row_mask:0xf bank_mask:0xf
	v_add_f32_e32 v49, v49, v54
	v_mov_b32_dpp v55, v55 quad_perm:[2,3,0,1] row_mask:0xf bank_mask:0xf
	v_mov_b32_e32 v54, v49
	v_add_f32_e32 v34, v34, v55
	v_mov_b32_e32 v55, v34
	v_mov_b32_dpp v54, v54 quad_perm:[2,3,0,1] row_mask:0xf bank_mask:0xf
	v_add_f32_e32 v49, v49, v54
	v_mov_b32_dpp v55, v55 row_half_mirror row_mask:0xf bank_mask:0xf
	v_mov_b32_e32 v54, v49
	v_add_f32_e32 v34, v34, v55
	v_mov_b32_e32 v55, v34
	v_mov_b32_dpp v54, v54 row_half_mirror row_mask:0xf bank_mask:0xf
	v_add_f32_e32 v49, v49, v54
	v_mov_b32_dpp v55, v55 row_mirror row_mask:0xf bank_mask:0xf
	v_mov_b32_e32 v56, v49
	v_add_f32_e32 v34, v34, v55
	s_nop 0
	v_mov_b32_dpp v56, v56 row_mirror row_mask:0xf bank_mask:0xf
	v_readlane_b32 s0, v34, 0
	v_readlane_b32 s6, v34, 16
	v_readlane_b32 s1, v34, 32
	v_readlane_b32 s24, v34, 48
	v_add_f32_e32 v34, v49, v56
	v_mov_b32_e32 v54, s6
	v_mov_b32_e32 v55, s24
	v_readlane_b32 s6, v34, 16
	v_readlane_b32 s24, v34, 48
	v_pk_add_f32 v[54:55], s[0:1], v[54:55]
	v_readlane_b32 s0, v34, 0
	v_readlane_b32 s1, v34, 32
	v_mov_b32_e32 v56, s6
	v_mov_b32_e32 v57, s24
	v_pk_add_f32 v[56:57], s[0:1], v[56:57]
	v_mov_b32_e32 v59, v54
	v_mov_b32_e32 v58, v56
	v_mov_b32_e32 v54, v57
	v_pk_add_f32 v[54:55], v[58:59], v[54:55]
	s_nop 0
	v_pk_fma_f32 v[54:55], v[54:55], s[22:23], v[42:43] op_sel_hi:[1,0,0]
	s_nop 0
	v_mul_f32_e32 v34, 0x4b800000, v55
	v_cmp_gt_f32_e32 vcc, s23, v55
	s_nop 1
	v_cndmask_b32_e32 v34, v55, v34, vcc
	v_rsq_f32_e32 v34, v34
	s_nop 0
	v_mul_f32_e32 v49, 0x45800000, v34
	v_cndmask_b32_e32 v34, v34, v49, vcc
	v_cmp_gt_f32_e32 vcc, s23, v54
	v_mul_f32_e32 v49, 0x4b800000, v54
	v_pk_mul_f32 v[32:33], v[32:33], v[34:35] op_sel_hi:[1,0]
	v_cndmask_b32_e32 v49, v54, v49, vcc
	v_rsq_f32_e32 v49, v49
	v_pk_mul_f32 v[30:31], v[30:31], v[34:35] op_sel_hi:[1,0]
	v_mul_f32_e32 v56, 0x45800000, v49
	v_cndmask_b32_e32 v56, v49, v56, vcc
	v_pk_mul_f32 v[32:33], v[32:33], v[86:87]
	v_pk_mul_f32 v[30:31], v[30:31], v[84:85]
	v_cvt_pk_bf16_f32 v33, v32, v33
	v_cvt_pk_bf16_f32 v32, v30, v31
	global_store_dwordx2 v[44:45], v[32:33], off
	v_pk_mul_f32 v[28:29], v[28:29], v[34:35] op_sel_hi:[1,0]
	v_pk_mul_f32 v[26:27], v[26:27], v[34:35] op_sel_hi:[1,0]
	v_pk_mul_f32 v[28:29], v[28:29], v[90:91]
	v_pk_mul_f32 v[26:27], v[26:27], v[88:89]
	v_cvt_pk_bf16_f32 v29, v28, v29
	v_cvt_pk_bf16_f32 v28, v26, v27
	global_store_dwordx2 v[44:45], v[28:29], off offset:512
	v_pk_mul_f32 v[24:25], v[24:25], v[34:35] op_sel_hi:[1,0]
	v_pk_mul_f32 v[22:23], v[22:23], v[34:35] op_sel_hi:[1,0]
	v_pk_mul_f32 v[24:25], v[24:25], v[94:95]
	v_pk_mul_f32 v[22:23], v[22:23], v[92:93]
	v_cvt_pk_bf16_f32 v25, v24, v25
	v_cvt_pk_bf16_f32 v24, v22, v23
	global_store_dwordx2 v[44:45], v[24:25], off offset:1024
	v_pk_mul_f32 v[20:21], v[20:21], v[34:35] op_sel_hi:[1,0]
	v_pk_mul_f32 v[18:19], v[18:19], v[34:35] op_sel_hi:[1,0]
	v_pk_mul_f32 v[20:21], v[20:21], v[98:99]
	v_pk_mul_f32 v[18:19], v[18:19], v[96:97]
	v_cvt_pk_bf16_f32 v21, v20, v21
	v_cvt_pk_bf16_f32 v20, v18, v19
	global_store_dwordx2 v[44:45], v[20:21], off offset:1536
	v_pk_mul_f32 v[16:17], v[16:17], v[56:57] op_sel_hi:[1,0]
	v_pk_mul_f32 v[14:15], v[14:15], v[56:57] op_sel_hi:[1,0]
	v_pk_mul_f32 v[16:17], v[16:17], v[86:87]
	v_pk_mul_f32 v[14:15], v[14:15], v[84:85]
	v_cvt_pk_bf16_f32 v17, v16, v17
	v_cvt_pk_bf16_f32 v16, v14, v15
	global_store_dwordx2 v[44:45], v[16:17], off offset:2048
	v_pk_mul_f32 v[12:13], v[12:13], v[56:57] op_sel_hi:[1,0]
	v_pk_mul_f32 v[10:11], v[10:11], v[56:57] op_sel_hi:[1,0]
	v_pk_mul_f32 v[12:13], v[12:13], v[90:91]
	v_pk_mul_f32 v[10:11], v[10:11], v[88:89]
	v_cvt_pk_bf16_f32 v13, v12, v13
	v_cvt_pk_bf16_f32 v12, v10, v11
	global_store_dwordx2 v[44:45], v[12:13], off offset:2560
	v_pk_mul_f32 v[8:9], v[8:9], v[56:57] op_sel_hi:[1,0]
	v_pk_mul_f32 v[6:7], v[6:7], v[56:57] op_sel_hi:[1,0]
	v_pk_mul_f32 v[8:9], v[8:9], v[94:95]
	v_pk_mul_f32 v[6:7], v[6:7], v[92:93]
	v_cvt_pk_bf16_f32 v9, v8, v9
	v_cvt_pk_bf16_f32 v8, v6, v7
	global_store_dwordx2 v[44:45], v[8:9], off offset:3072
	v_pk_mul_f32 v[4:5], v[4:5], v[56:57] op_sel_hi:[1,0]
	v_pk_mul_f32 v[2:3], v[2:3], v[56:57] op_sel_hi:[1,0]
	v_pk_mul_f32 v[4:5], v[4:5], v[98:99]
	v_pk_mul_f32 v[2:3], v[2:3], v[96:97]
	v_cvt_pk_bf16_f32 v5, v4, v5
	v_cvt_pk_bf16_f32 v4, v2, v3
	global_store_dwordx2 v[44:45], v[4:5], off offset:3584
	s_branch .LBB0_7

.LBB0_1129:
	s_waitcnt vmcnt(0) lgkmcnt(0)
	s_barrier
	s_branch .Lp_scanexit

.Lp_scanexit:
	s_waitcnt vmcnt(0)
	s_barrier
	s_and_saveexec_b64 s[10:11], s[92:93]
	v_readlane_b32 s40, v246, 32
	v_readlane_b32 s46, v246, 38
	v_readlane_b32 s47, v246, 39
	v_readlane_b32 s48, v246, 40
	v_readlane_b32 s49, v246, 41
	v_readlane_b32 s52, v246, 44
	v_readlane_b32 s53, v246, 45
	v_readlane_b32 s54, v246, 46
	v_readlane_b32 s55, v246, 47
	v_readlane_b32 s41, v246, 33
	v_readlane_b32 s42, v246, 34
	v_readlane_b32 s43, v246, 35
	v_readlane_b32 s44, v246, 36
	v_readlane_b32 s45, v246, 37
	v_readlane_b32 s50, v246, 42
	v_readlane_b32 s51, v246, 43
	s_cbranch_execz .LBB0_1221
	s_add_i32 s12, 0, 0x25e00
	v_mov_b32_e32 v0, s12
	s_waitcnt vmcnt(0) expcnt(0) lgkmcnt(0)
	ds_read_b32 v2, v0
	s_add_i32 s12, 0, 0x25e04
	v_mov_b32_e32 v0, s12
	ds_read_b32 v0, v0
	s_waitcnt lgkmcnt(1)
	v_cmp_ne_u32_e32 vcc, 0, v2
	s_cbranch_vccnz .LBB0_1185
	s_mov_b32 s23, 1
	v_mov_b32_e32 v16, 0
	s_branch .LBB0_1173
